# pipelined prologue x/p conversion loops; ssq back to atomics (no extra reduce phase)
# speedup vs baseline: 1.0599x; 1.0033x over previous
; __device__ __forceinline__ unsigned cvt_pk_bf16(float lo, float hi) { unsigned r; asm volatile("v_cvt_pk_bf16_f32 %0, %1, %2" : "=v"(r) : "v"(lo), "v"(hi)); return r; }
; __device__ void phase_prologue(KP P, LAS unsigned char* lds) {
;     ...
;     bf16_t* xb = (bf16_t*)(ws + OFF_XB); float* ssq = (float*)(ws + OFF_SSQ);
; #pragma unroll 8
;     for (int row = gw; row < MTOK; row += nw) { float s = 0.f;
; #pragma unroll
;         for (int i = 0; i < 4; ++i) { const int col = lane * 4 + 256 * i; const f32x4 v = __builtin_nontemporal_load((const f32x4*)(P->x + (size_t)row * 1024 + col));
;             s += v.x * v.x + v.y * v.y + v.z * v.z + v.w * v.w; u32x2 w; w.x = cvt_pk_bf16(v.x, v.y); w.y = cvt_pk_bf16(v.z, v.w); *(u32x2*)(xb + (size_t)row * 1024 + col) = w; }
; #pragma unroll
;         for (int d = 32; d >= 1; d >>= 1) s += __shfl_xor(s, d);
;         if (lane == 0) ssq[row] = s; }
.LBB0_56:
	s_or_b64 exec, exec, s[6:7]
	v_cmp_gt_i32_e32 vcc, s71, v28
	s_and_saveexec_b64 s[6:7], vcc
	s_cbranch_execz .LBB0_64
	v_cvt_f32_u32_e32 v2, s4
	s_waitcnt lgkmcnt(0)
	s_add_u32 s8, s90, 0x8700000
	s_addc_u32 s9, s91, 0
	s_sub_i32 s3, 0, s4
	v_rcp_iflag_f32_e32 v2, v2
	v_add_u32_e32 v29, s4, v28
	v_max_i32_e32 v0, 0x8000, v29
	v_cmp_gt_i32_e32 vcc, s71, v29
	v_mul_f32_e32 v2, 0x4f7ffffe, v2
	v_cvt_u32_f32_e32 v2, v2
	v_cndmask_b32_e64 v1, 1, 2, vcc
	v_subb_co_u32_e32 v0, vcc, v0, v29, vcc
	v_mul_lo_u32 v3, s3, v2
	v_mul_hi_u32 v3, v2, v3
	v_add_u32_e32 v2, v2, v3
	v_mul_hi_u32 v2, v0, v2
	v_mul_lo_u32 v3, v2, s4
	v_sub_u32_e32 v0, v0, v3
	v_cmp_le_u32_e32 vcc, s4, v0
	v_add_u32_e32 v3, 1, v2
	s_mov_b64 s[12:13], -1
	v_cndmask_b32_e32 v2, v2, v3, vcc
	v_subrev_u32_e32 v3, s4, v0
	v_cndmask_b32_e32 v0, v0, v3, vcc
	v_cmp_le_u32_e32 vcc, s4, v0
	v_add_u32_e32 v0, 1, v2
	s_nop 0
	v_cndmask_b32_e32 v0, v2, v0, vcc
	v_add_u32_e32 v2, v1, v0
	v_cmp_lt_u32_e32 vcc, 1, v2
	v_mov_b32_e32 v0, v28
	s_and_saveexec_b64 s[10:11], vcc
	s_cbranch_execz .LBB0_61
	v_and_b32_e32 v3, -2, v2
	s_lshl_b32 s3, s1, 10
	s_mov_b32 s5, s3
	s_mov_b64 s[12:13], 0
	v_mov_b32_e32 v4, v3
	v_mov_b64_e32 v[0:1], v[28:29]

; __device__ __forceinline__ unsigned cvt_pk_bf16(float lo, float hi) { unsigned r; asm volatile("v_cvt_pk_bf16_f32 %0, %1, %2" : "=v"(r) : "v"(lo), "v"(hi)); return r; }
; __device__ void phase_prologue(KP P, LAS unsigned char* lds) {
;     ...
;     bf16_t* xb = (bf16_t*)(ws + OFF_XB); float* ssq = (float*)(ws + OFF_SSQ);
; #pragma unroll 8
;     for (int row = gw; row < MTOK; row += nw) { float s = 0.f;
; #pragma unroll
;         for (int i = 0; i < 4; ++i) { const int col = lane * 4 + 256 * i; const f32x4 v = __builtin_nontemporal_load((const f32x4*)(P->x + (size_t)row * 1024 + col));
;             s += v.x * v.x + v.y * v.y + v.z * v.z + v.w * v.w; u32x2 w; w.x = cvt_pk_bf16(v.x, v.y); w.y = cvt_pk_bf16(v.z, v.w); *(u32x2*)(xb + (size_t)row * 1024 + col) = w; }
; #pragma unroll
;         for (int d = 32; d >= 1; d >>= 1) s += __shfl_xor(s, d);
;         if (lane == 0) ssq[row] = s; }
.LBB0_525:
	s_or_b64 exec, exec, s[6:7]
	s_cmpk_lg_u32 s54, 0x100
	s_cbranch_scc1 .Lpro_generic
	s_load_dwordx2 s[8:9], s[36:37], 0x0
	s_load_dwordx2 s[18:19], s[36:37], 0x8
	v_and_b32_e32 v160, 63, v208
	v_lshrrev_b32_e32 v161, 6, v208
	v_lshlrev_b32_e32 v162, 4, v160
	v_lshlrev_b32_e32 v163, 3, v160
	v_mov_b32_e32 v164, 0
	v_readfirstlane_b32 s1, v161
	s_lshl_b32 s3, s2, 3
	s_add_i32 s3, s3, s1
	s_mov_b32 s4, s3
	s_mov_b32 s5, 0
	s_lshl_b64 s[10:11], s[4:5], 12
	s_lshl_b64 s[12:13], s[4:5], 11
	s_lshl_b64 s[14:15], s[4:5], 2
	s_waitcnt lgkmcnt(0)
	s_add_u32 s8, s8, s10
	s_addc_u32 s9, s9, s11
	s_add_u32 s10, s90, 0x4700000
	s_addc_u32 s11, s91, 0
	s_add_u32 s10, s10, s12
	s_addc_u32 s11, s11, s13
	s_add_u32 s12, s90, 0x8700000
	s_addc_u32 s13, s91, 0
	s_add_u32 s12, s12, s14
	s_addc_u32 s13, s13, s15
	s_add_u32 s14, s8, 0x0
	s_addc_u32 s15, s9, 0
	global_load_dwordx4 v[0:3], v162, s[14:15] nt
	global_load_dwordx4 v[4:7], v162, s[14:15] offset:1024 nt
	global_load_dwordx4 v[8:11], v162, s[14:15] offset:2048 nt
	global_load_dwordx4 v[12:15], v162, s[14:15] offset:3072 nt
	s_add_u32 s14, s8, 0x800000
	s_addc_u32 s15, s9, 0
	global_load_dwordx4 v[16:19], v162, s[14:15] nt
	global_load_dwordx4 v[20:23], v162, s[14:15] offset:1024 nt
	global_load_dwordx4 v[24:27], v162, s[14:15] offset:2048 nt
	global_load_dwordx4 v[28:31], v162, s[14:15] offset:3072 nt
	s_add_u32 s14, s8, 0x1000000
	s_addc_u32 s15, s9, 0
	global_load_dwordx4 v[32:35], v162, s[14:15] nt
	global_load_dwordx4 v[36:39], v162, s[14:15] offset:1024 nt
	global_load_dwordx4 v[40:43], v162, s[14:15] offset:2048 nt
	global_load_dwordx4 v[44:47], v162, s[14:15] offset:3072 nt
	s_add_u32 s14, s8, 0x1800000
	s_addc_u32 s15, s9, 0
	global_load_dwordx4 v[48:51], v162, s[14:15] nt
	global_load_dwordx4 v[52:55], v162, s[14:15] offset:1024 nt
	global_load_dwordx4 v[56:59], v162, s[14:15] offset:2048 nt
	global_load_dwordx4 v[60:63], v162, s[14:15] offset:3072 nt
	s_add_u32 s14, s8, 0x2000000
	s_addc_u32 s15, s9, 0
	global_load_dwordx4 v[64:67], v162, s[14:15] nt
	global_load_dwordx4 v[68:71], v162, s[14:15] offset:1024 nt
	global_load_dwordx4 v[72:75], v162, s[14:15] offset:2048 nt
	global_load_dwordx4 v[76:79], v162, s[14:15] offset:3072 nt
	s_add_u32 s14, s8, 0x2800000
	s_addc_u32 s15, s9, 0
	global_load_dwordx4 v[80:83], v162, s[14:15] nt
	global_load_dwordx4 v[84:87], v162, s[14:15] offset:1024 nt
	global_load_dwordx4 v[88:91], v162, s[14:15] offset:2048 nt
	global_load_dwordx4 v[92:95], v162, s[14:15] offset:3072 nt
	s_add_u32 s14, s8, 0x3000000
	s_addc_u32 s15, s9, 0
	global_load_dwordx4 v[96:99], v162, s[14:15] nt
	global_load_dwordx4 v[100:103], v162, s[14:15] offset:1024 nt
	global_load_dwordx4 v[104:107], v162, s[14:15] offset:2048 nt
	global_load_dwordx4 v[108:111], v162, s[14:15] offset:3072 nt
	s_add_u32 s14, s8, 0x3800000
	s_addc_u32 s15, s9, 0
	global_load_dwordx4 v[112:115], v162, s[14:15] nt
	global_load_dwordx4 v[116:119], v162, s[14:15] offset:1024 nt
	global_load_dwordx4 v[120:123], v162, s[14:15] offset:2048 nt
	global_load_dwordx4 v[124:127], v162, s[14:15] offset:3072 nt
	s_waitcnt vmcnt(28)
	s_add_u32 s16, s10, 0x0
	s_addc_u32 s17, s11, 0
	v_mul_f32_e32 v128, v1, v1
	v_fmac_f32_e32 v128, v0, v0
	v_fmac_f32_e32 v128, v2, v2
	v_fmac_f32_e32 v128, v3, v3
	v_mul_f32_e32 v129, v5, v5
	v_fmac_f32_e32 v129, v4, v4
	v_fmac_f32_e32 v129, v6, v6
	v_fmac_f32_e32 v129, v7, v7
	v_mul_f32_e32 v130, v9, v9
	v_fmac_f32_e32 v130, v8, v8
	v_fmac_f32_e32 v130, v10, v10
	v_fmac_f32_e32 v130, v11, v11
	v_mul_f32_e32 v131, v13, v13
	v_fmac_f32_e32 v131, v12, v12
	v_fmac_f32_e32 v131, v14, v14
	v_fmac_f32_e32 v131, v15, v15
	v_add_f32_e32 v128, v128, v129
	v_add_f32_e32 v128, v128, v130
	v_add_f32_e32 v128, v128, v131
	v_cvt_pk_bf16_f32 v132, v0, v1
	v_cvt_pk_bf16_f32 v133, v2, v3
	v_cvt_pk_bf16_f32 v134, v4, v5
	v_cvt_pk_bf16_f32 v135, v6, v7
	v_cvt_pk_bf16_f32 v136, v8, v9
	v_cvt_pk_bf16_f32 v137, v10, v11
	v_cvt_pk_bf16_f32 v138, v12, v13
	v_cvt_pk_bf16_f32 v139, v14, v15
	global_store_dwordx2 v163, v[132:133], s[16:17]
	global_store_dwordx2 v163, v[134:135], s[16:17] offset:512
	global_store_dwordx2 v163, v[136:137], s[16:17] offset:1024
	global_store_dwordx2 v163, v[138:139], s[16:17] offset:1536
	v_add_f32_dpp v128, v128, v128 quad_perm:[1,0,3,2] row_mask:0xf bank_mask:0xf
	s_nop 1
	v_add_f32_dpp v128, v128, v128 quad_perm:[2,3,0,1] row_mask:0xf bank_mask:0xf
	s_nop 1
	v_add_f32_dpp v128, v128, v128 row_half_mirror row_mask:0xf bank_mask:0xf
	s_nop 1
	v_add_f32_dpp v128, v128, v128 row_mirror row_mask:0xf bank_mask:0xf
	s_nop 1
	v_add_f32_dpp v128, v128, v128 row_bcast:15 row_mask:0xa bank_mask:0xf
	s_nop 1
	v_add_f32_dpp v128, v128, v128 row_bcast:31 row_mask:0xc bank_mask:0xf
	s_nop 1
	v_readlane_b32 s1, v128, 63
	s_add_u32 s14, s12, 0x0
	s_addc_u32 s15, s13, 0
	s_mov_b64 exec, 1
	v_mov_b32_e32 v129, s1
	global_store_dword v164, v129, s[14:15]
	s_mov_b64 exec, -1
	s_add_u32 s14, s8, 0x4000000
	s_addc_u32 s15, s9, 0
	global_load_dwordx4 v[0:3], v162, s[14:15] nt
	global_load_dwordx4 v[4:7], v162, s[14:15] offset:1024 nt
	global_load_dwordx4 v[8:11], v162, s[14:15] offset:2048 nt
	global_load_dwordx4 v[12:15], v162, s[14:15] offset:3072 nt
	s_waitcnt vmcnt(33)
; __device__ __forceinline__ unsigned cvt_pk_bf16(float lo, float hi) { unsigned r; asm volatile("v_cvt_pk_bf16_f32 %0, %1, %2" : "=v"(r) : "v"(lo), "v"(hi)); return r; }
; __device__ void phase_prologue(KP P, LAS unsigned char* lds) {
;     ...
;     for (int row = gw; row < MTOK; row += nw) { float s = 0.f;
; #pragma unroll
;         for (int i = 0; i < 4; ++i) { const int col = lane * 4 + 256 * i; const f32x4 v = __builtin_nontemporal_load((const f32x4*)(P->x + (size_t)row * 1024 + col));
;             s += v.x * v.x + v.y * v.y + v.z * v.z + v.w * v.w; u32x2 w; w.x = cvt_pk_bf16(v.x, v.y); w.y = cvt_pk_bf16(v.z, v.w); *(u32x2*)(xb + (size_t)row * 1024 + col) = w; }
; #pragma unroll
;         for (int d = 32; d >= 1; d >>= 1) s += __shfl_xor(s, d);
;         if (lane == 0) ssq[row] = s; }
	s_add_u32 s16, s10, 0x400000
	s_addc_u32 s17, s11, 0
	v_mul_f32_e32 v128, v17, v17
	v_fmac_f32_e32 v128, v16, v16
	v_fmac_f32_e32 v128, v18, v18
	v_fmac_f32_e32 v128, v19, v19
	v_mul_f32_e32 v129, v21, v21
	v_fmac_f32_e32 v129, v20, v20
	v_fmac_f32_e32 v129, v22, v22
	v_fmac_f32_e32 v129, v23, v23
	v_mul_f32_e32 v130, v25, v25
	v_fmac_f32_e32 v130, v24, v24
	v_fmac_f32_e32 v130, v26, v26
	v_fmac_f32_e32 v130, v27, v27
	v_mul_f32_e32 v131, v29, v29
	v_fmac_f32_e32 v131, v28, v28
	v_fmac_f32_e32 v131, v30, v30
	v_fmac_f32_e32 v131, v31, v31
	v_add_f32_e32 v128, v128, v129
	v_add_f32_e32 v128, v128, v130
	v_add_f32_e32 v128, v128, v131
	v_cvt_pk_bf16_f32 v132, v16, v17
	v_cvt_pk_bf16_f32 v133, v18, v19
	v_cvt_pk_bf16_f32 v134, v20, v21
	v_cvt_pk_bf16_f32 v135, v22, v23
	v_cvt_pk_bf16_f32 v136, v24, v25
	v_cvt_pk_bf16_f32 v137, v26, v27
	v_cvt_pk_bf16_f32 v138, v28, v29
	v_cvt_pk_bf16_f32 v139, v30, v31
	global_store_dwordx2 v163, v[132:133], s[16:17]
	global_store_dwordx2 v163, v[134:135], s[16:17] offset:512
	global_store_dwordx2 v163, v[136:137], s[16:17] offset:1024
	global_store_dwordx2 v163, v[138:139], s[16:17] offset:1536
	v_add_f32_dpp v128, v128, v128 quad_perm:[1,0,3,2] row_mask:0xf bank_mask:0xf
	s_nop 1
	v_add_f32_dpp v128, v128, v128 quad_perm:[2,3,0,1] row_mask:0xf bank_mask:0xf
	s_nop 1
	v_add_f32_dpp v128, v128, v128 row_half_mirror row_mask:0xf bank_mask:0xf
	s_nop 1
	v_add_f32_dpp v128, v128, v128 row_mirror row_mask:0xf bank_mask:0xf
	s_nop 1
	v_add_f32_dpp v128, v128, v128 row_bcast:15 row_mask:0xa bank_mask:0xf
	s_nop 1
	v_add_f32_dpp v128, v128, v128 row_bcast:31 row_mask:0xc bank_mask:0xf
	s_nop 1
	v_readlane_b32 s1, v128, 63
	s_add_u32 s14, s12, 0x2000
	s_addc_u32 s15, s13, 0
	s_mov_b64 exec, 1
	v_mov_b32_e32 v129, s1
	global_store_dword v164, v129, s[14:15]
	s_mov_b64 exec, -1
	s_add_u32 s14, s8, 0x4800000
	s_addc_u32 s15, s9, 0
	global_load_dwordx4 v[16:19], v162, s[14:15] nt
	global_load_dwordx4 v[20:23], v162, s[14:15] offset:1024 nt
	global_load_dwordx4 v[24:27], v162, s[14:15] offset:2048 nt
	global_load_dwordx4 v[28:31], v162, s[14:15] offset:3072 nt
	s_waitcnt vmcnt(38)
	s_add_u32 s16, s10, 0x800000
	s_addc_u32 s17, s11, 0
	v_mul_f32_e32 v128, v33, v33
	v_fmac_f32_e32 v128, v32, v32
	v_fmac_f32_e32 v128, v34, v34
	v_fmac_f32_e32 v128, v35, v35
	v_mul_f32_e32 v129, v37, v37
	v_fmac_f32_e32 v129, v36, v36
	v_fmac_f32_e32 v129, v38, v38
	v_fmac_f32_e32 v129, v39, v39
	v_mul_f32_e32 v130, v41, v41
	v_fmac_f32_e32 v130, v40, v40
	v_fmac_f32_e32 v130, v42, v42
	v_fmac_f32_e32 v130, v43, v43
	v_mul_f32_e32 v131, v45, v45
	v_fmac_f32_e32 v131, v44, v44
	v_fmac_f32_e32 v131, v46, v46
	v_fmac_f32_e32 v131, v47, v47
	v_add_f32_e32 v128, v128, v129
	v_add_f32_e32 v128, v128, v130
	v_add_f32_e32 v128, v128, v131
	v_cvt_pk_bf16_f32 v132, v32, v33
	v_cvt_pk_bf16_f32 v133, v34, v35
	v_cvt_pk_bf16_f32 v134, v36, v37
	v_cvt_pk_bf16_f32 v135, v38, v39
	v_cvt_pk_bf16_f32 v136, v40, v41
	v_cvt_pk_bf16_f32 v137, v42, v43
	v_cvt_pk_bf16_f32 v138, v44, v45
	v_cvt_pk_bf16_f32 v139, v46, v47
	global_store_dwordx2 v163, v[132:133], s[16:17]
	global_store_dwordx2 v163, v[134:135], s[16:17] offset:512
	global_store_dwordx2 v163, v[136:137], s[16:17] offset:1024
	global_store_dwordx2 v163, v[138:139], s[16:17] offset:1536
	v_add_f32_dpp v128, v128, v128 quad_perm:[1,0,3,2] row_mask:0xf bank_mask:0xf
	s_nop 1
	v_add_f32_dpp v128, v128, v128 quad_perm:[2,3,0,1] row_mask:0xf bank_mask:0xf
	s_nop 1
	v_add_f32_dpp v128, v128, v128 row_half_mirror row_mask:0xf bank_mask:0xf
	s_nop 1
	v_add_f32_dpp v128, v128, v128 row_mirror row_mask:0xf bank_mask:0xf
	s_nop 1
	v_add_f32_dpp v128, v128, v128 row_bcast:15 row_mask:0xa bank_mask:0xf
	s_nop 1
	v_add_f32_dpp v128, v128, v128 row_bcast:31 row_mask:0xc bank_mask:0xf
	s_nop 1
	v_readlane_b32 s1, v128, 63
	s_add_u32 s14, s12, 0x4000
	s_addc_u32 s15, s13, 0
	s_mov_b64 exec, 1
	v_mov_b32_e32 v129, s1
	global_store_dword v164, v129, s[14:15]
	s_mov_b64 exec, -1
	s_add_u32 s14, s8, 0x5000000
	s_addc_u32 s15, s9, 0
	global_load_dwordx4 v[32:35], v162, s[14:15] nt
	global_load_dwordx4 v[36:39], v162, s[14:15] offset:1024 nt
	global_load_dwordx4 v[40:43], v162, s[14:15] offset:2048 nt
	global_load_dwordx4 v[44:47], v162, s[14:15] offset:3072 nt
	s_waitcnt vmcnt(43)
	s_add_u32 s16, s10, 0xc00000
	s_addc_u32 s17, s11, 0
	v_mul_f32_e32 v128, v49, v49
	v_fmac_f32_e32 v128, v48, v48
	v_fmac_f32_e32 v128, v50, v50
	v_fmac_f32_e32 v128, v51, v51
	v_mul_f32_e32 v129, v53, v53
	v_fmac_f32_e32 v129, v52, v52
	v_fmac_f32_e32 v129, v54, v54
	v_fmac_f32_e32 v129, v55, v55
	v_mul_f32_e32 v130, v57, v57
	v_fmac_f32_e32 v130, v56, v56
	v_fmac_f32_e32 v130, v58, v58
	v_fmac_f32_e32 v130, v59, v59
	v_mul_f32_e32 v131, v61, v61
	v_fmac_f32_e32 v131, v60, v60
	v_fmac_f32_e32 v131, v62, v62
	v_fmac_f32_e32 v131, v63, v63
	v_add_f32_e32 v128, v128, v129
	v_add_f32_e32 v128, v128, v130
	v_add_f32_e32 v128, v128, v131
	v_cvt_pk_bf16_f32 v132, v48, v49
	v_cvt_pk_bf16_f32 v133, v50, v51
	v_cvt_pk_bf16_f32 v134, v52, v53
	v_cvt_pk_bf16_f32 v135, v54, v55
	v_cvt_pk_bf16_f32 v136, v56, v57
	v_cvt_pk_bf16_f32 v137, v58, v59
	v_cvt_pk_bf16_f32 v138, v60, v61
	v_cvt_pk_bf16_f32 v139, v62, v63
	global_store_dwordx2 v163, v[132:133], s[16:17]
	global_store_dwordx2 v163, v[134:135], s[16:17] offset:512
	global_store_dwordx2 v163, v[136:137], s[16:17] offset:1024
	global_store_dwordx2 v163, v[138:139], s[16:17] offset:1536
	v_add_f32_dpp v128, v128, v128 quad_perm:[1,0,3,2] row_mask:0xf bank_mask:0xf
	s_nop 1
	v_add_f32_dpp v128, v128, v128 quad_perm:[2,3,0,1] row_mask:0xf bank_mask:0xf
	s_nop 1
	v_add_f32_dpp v128, v128, v128 row_half_mirror row_mask:0xf bank_mask:0xf
	s_nop 1
	v_add_f32_dpp v128, v128, v128 row_mirror row_mask:0xf bank_mask:0xf
	s_nop 1
	v_add_f32_dpp v128, v128, v128 row_bcast:15 row_mask:0xa bank_mask:0xf
	s_nop 1
	v_add_f32_dpp v128, v128, v128 row_bcast:31 row_mask:0xc bank_mask:0xf
	s_nop 1
	v_readlane_b32 s1, v128, 63
	s_add_u32 s14, s12, 0x6000
	s_addc_u32 s15, s13, 0
	s_mov_b64 exec, 1
	v_mov_b32_e32 v129, s1
	global_store_dword v164, v129, s[14:15]
	s_mov_b64 exec, -1
	s_add_u32 s14, s8, 0x5800000
	s_addc_u32 s15, s9, 0
	global_load_dwordx4 v[48:51], v162, s[14:15] nt
	global_load_dwordx4 v[52:55], v162, s[14:15] offset:1024 nt
	global_load_dwordx4 v[56:59], v162, s[14:15] offset:2048 nt
	global_load_dwordx4 v[60:63], v162, s[14:15] offset:3072 nt
	s_waitcnt vmcnt(48)
; __device__ __forceinline__ unsigned cvt_pk_bf16(float lo, float hi) { unsigned r; asm volatile("v_cvt_pk_bf16_f32 %0, %1, %2" : "=v"(r) : "v"(lo), "v"(hi)); return r; }
; __device__ void phase_prologue(KP P, LAS unsigned char* lds) {
;     ...
;     for (int row = gw; row < MTOK; row += nw) { float s = 0.f;
; #pragma unroll
;         for (int i = 0; i < 4; ++i) { const int col = lane * 4 + 256 * i; const f32x4 v = __builtin_nontemporal_load((const f32x4*)(P->x + (size_t)row * 1024 + col));
;             s += v.x * v.x + v.y * v.y + v.z * v.z + v.w * v.w; u32x2 w; w.x = cvt_pk_bf16(v.x, v.y); w.y = cvt_pk_bf16(v.z, v.w); *(u32x2*)(xb + (size_t)row * 1024 + col) = w; }
; #pragma unroll
;         for (int d = 32; d >= 1; d >>= 1) s += __shfl_xor(s, d);
;         if (lane == 0) ssq[row] = s; }
	s_add_u32 s16, s10, 0x1000000
	s_addc_u32 s17, s11, 0
	v_mul_f32_e32 v128, v65, v65
	v_fmac_f32_e32 v128, v64, v64
	v_fmac_f32_e32 v128, v66, v66
	v_fmac_f32_e32 v128, v67, v67
	v_mul_f32_e32 v129, v69, v69
	v_fmac_f32_e32 v129, v68, v68
	v_fmac_f32_e32 v129, v70, v70
	v_fmac_f32_e32 v129, v71, v71
	v_mul_f32_e32 v130, v73, v73
	v_fmac_f32_e32 v130, v72, v72
	v_fmac_f32_e32 v130, v74, v74
	v_fmac_f32_e32 v130, v75, v75
	v_mul_f32_e32 v131, v77, v77
	v_fmac_f32_e32 v131, v76, v76
	v_fmac_f32_e32 v131, v78, v78
	v_fmac_f32_e32 v131, v79, v79
	v_add_f32_e32 v128, v128, v129
	v_add_f32_e32 v128, v128, v130
	v_add_f32_e32 v128, v128, v131
	v_cvt_pk_bf16_f32 v132, v64, v65
	v_cvt_pk_bf16_f32 v133, v66, v67
	v_cvt_pk_bf16_f32 v134, v68, v69
	v_cvt_pk_bf16_f32 v135, v70, v71
	v_cvt_pk_bf16_f32 v136, v72, v73
	v_cvt_pk_bf16_f32 v137, v74, v75
	v_cvt_pk_bf16_f32 v138, v76, v77
	v_cvt_pk_bf16_f32 v139, v78, v79
	global_store_dwordx2 v163, v[132:133], s[16:17]
	global_store_dwordx2 v163, v[134:135], s[16:17] offset:512
	global_store_dwordx2 v163, v[136:137], s[16:17] offset:1024
	global_store_dwordx2 v163, v[138:139], s[16:17] offset:1536
	v_add_f32_dpp v128, v128, v128 quad_perm:[1,0,3,2] row_mask:0xf bank_mask:0xf
	s_nop 1
	v_add_f32_dpp v128, v128, v128 quad_perm:[2,3,0,1] row_mask:0xf bank_mask:0xf
	s_nop 1
	v_add_f32_dpp v128, v128, v128 row_half_mirror row_mask:0xf bank_mask:0xf
	s_nop 1
	v_add_f32_dpp v128, v128, v128 row_mirror row_mask:0xf bank_mask:0xf
	s_nop 1
	v_add_f32_dpp v128, v128, v128 row_bcast:15 row_mask:0xa bank_mask:0xf
	s_nop 1
	v_add_f32_dpp v128, v128, v128 row_bcast:31 row_mask:0xc bank_mask:0xf
	s_nop 1
	v_readlane_b32 s1, v128, 63
	s_add_u32 s14, s12, 0x8000
	s_addc_u32 s15, s13, 0
	s_mov_b64 exec, 1
	v_mov_b32_e32 v129, s1
	global_store_dword v164, v129, s[14:15]
	s_mov_b64 exec, -1
	s_add_u32 s14, s8, 0x6000000
	s_addc_u32 s15, s9, 0
	global_load_dwordx4 v[64:67], v162, s[14:15] nt
	global_load_dwordx4 v[68:71], v162, s[14:15] offset:1024 nt
	global_load_dwordx4 v[72:75], v162, s[14:15] offset:2048 nt
	global_load_dwordx4 v[76:79], v162, s[14:15] offset:3072 nt
	s_waitcnt vmcnt(53)
	s_add_u32 s16, s10, 0x1400000
	s_addc_u32 s17, s11, 0
	v_mul_f32_e32 v128, v81, v81
	v_fmac_f32_e32 v128, v80, v80
	v_fmac_f32_e32 v128, v82, v82
	v_fmac_f32_e32 v128, v83, v83
	v_mul_f32_e32 v129, v85, v85
	v_fmac_f32_e32 v129, v84, v84
	v_fmac_f32_e32 v129, v86, v86
	v_fmac_f32_e32 v129, v87, v87
	v_mul_f32_e32 v130, v89, v89
	v_fmac_f32_e32 v130, v88, v88
	v_fmac_f32_e32 v130, v90, v90
	v_fmac_f32_e32 v130, v91, v91
	v_mul_f32_e32 v131, v93, v93
	v_fmac_f32_e32 v131, v92, v92
	v_fmac_f32_e32 v131, v94, v94
	v_fmac_f32_e32 v131, v95, v95
	v_add_f32_e32 v128, v128, v129
	v_add_f32_e32 v128, v128, v130
	v_add_f32_e32 v128, v128, v131
	v_cvt_pk_bf16_f32 v132, v80, v81
	v_cvt_pk_bf16_f32 v133, v82, v83
	v_cvt_pk_bf16_f32 v134, v84, v85
	v_cvt_pk_bf16_f32 v135, v86, v87
	v_cvt_pk_bf16_f32 v136, v88, v89
	v_cvt_pk_bf16_f32 v137, v90, v91
	v_cvt_pk_bf16_f32 v138, v92, v93
	v_cvt_pk_bf16_f32 v139, v94, v95
	global_store_dwordx2 v163, v[132:133], s[16:17]
	global_store_dwordx2 v163, v[134:135], s[16:17] offset:512
	global_store_dwordx2 v163, v[136:137], s[16:17] offset:1024
	global_store_dwordx2 v163, v[138:139], s[16:17] offset:1536
	v_add_f32_dpp v128, v128, v128 quad_perm:[1,0,3,2] row_mask:0xf bank_mask:0xf
	s_nop 1
	v_add_f32_dpp v128, v128, v128 quad_perm:[2,3,0,1] row_mask:0xf bank_mask:0xf
	s_nop 1
	v_add_f32_dpp v128, v128, v128 row_half_mirror row_mask:0xf bank_mask:0xf
	s_nop 1
	v_add_f32_dpp v128, v128, v128 row_mirror row_mask:0xf bank_mask:0xf
	s_nop 1
	v_add_f32_dpp v128, v128, v128 row_bcast:15 row_mask:0xa bank_mask:0xf
	s_nop 1
	v_add_f32_dpp v128, v128, v128 row_bcast:31 row_mask:0xc bank_mask:0xf
	s_nop 1
	v_readlane_b32 s1, v128, 63
	s_add_u32 s14, s12, 0xa000
	s_addc_u32 s15, s13, 0
	s_mov_b64 exec, 1
	v_mov_b32_e32 v129, s1
	global_store_dword v164, v129, s[14:15]
	s_mov_b64 exec, -1
	s_add_u32 s14, s8, 0x6800000
	s_addc_u32 s15, s9, 0
	global_load_dwordx4 v[80:83], v162, s[14:15] nt
	global_load_dwordx4 v[84:87], v162, s[14:15] offset:1024 nt
	global_load_dwordx4 v[88:91], v162, s[14:15] offset:2048 nt
	global_load_dwordx4 v[92:95], v162, s[14:15] offset:3072 nt
	s_waitcnt vmcnt(58)
	s_add_u32 s16, s10, 0x1800000
	s_addc_u32 s17, s11, 0
	v_mul_f32_e32 v128, v97, v97
	v_fmac_f32_e32 v128, v96, v96
	v_fmac_f32_e32 v128, v98, v98
	v_fmac_f32_e32 v128, v99, v99
	v_mul_f32_e32 v129, v101, v101
	v_fmac_f32_e32 v129, v100, v100
	v_fmac_f32_e32 v129, v102, v102
	v_fmac_f32_e32 v129, v103, v103
	v_mul_f32_e32 v130, v105, v105
	v_fmac_f32_e32 v130, v104, v104
	v_fmac_f32_e32 v130, v106, v106
	v_fmac_f32_e32 v130, v107, v107
	v_mul_f32_e32 v131, v109, v109
	v_fmac_f32_e32 v131, v108, v108
	v_fmac_f32_e32 v131, v110, v110
	v_fmac_f32_e32 v131, v111, v111
	v_add_f32_e32 v128, v128, v129
	v_add_f32_e32 v128, v128, v130
	v_add_f32_e32 v128, v128, v131
	v_cvt_pk_bf16_f32 v132, v96, v97
	v_cvt_pk_bf16_f32 v133, v98, v99
	v_cvt_pk_bf16_f32 v134, v100, v101
	v_cvt_pk_bf16_f32 v135, v102, v103
	v_cvt_pk_bf16_f32 v136, v104, v105
	v_cvt_pk_bf16_f32 v137, v106, v107
	v_cvt_pk_bf16_f32 v138, v108, v109
	v_cvt_pk_bf16_f32 v139, v110, v111
	global_store_dwordx2 v163, v[132:133], s[16:17]
	global_store_dwordx2 v163, v[134:135], s[16:17] offset:512
	global_store_dwordx2 v163, v[136:137], s[16:17] offset:1024
	global_store_dwordx2 v163, v[138:139], s[16:17] offset:1536
	v_add_f32_dpp v128, v128, v128 quad_perm:[1,0,3,2] row_mask:0xf bank_mask:0xf
	s_nop 1
	v_add_f32_dpp v128, v128, v128 quad_perm:[2,3,0,1] row_mask:0xf bank_mask:0xf
	s_nop 1
	v_add_f32_dpp v128, v128, v128 row_half_mirror row_mask:0xf bank_mask:0xf
	s_nop 1
	v_add_f32_dpp v128, v128, v128 row_mirror row_mask:0xf bank_mask:0xf
	s_nop 1
	v_add_f32_dpp v128, v128, v128 row_bcast:15 row_mask:0xa bank_mask:0xf
	s_nop 1
	v_add_f32_dpp v128, v128, v128 row_bcast:31 row_mask:0xc bank_mask:0xf
	s_nop 1
	v_readlane_b32 s1, v128, 63
	s_add_u32 s14, s12, 0xc000
	s_addc_u32 s15, s13, 0
	s_mov_b64 exec, 1
	v_mov_b32_e32 v129, s1
	global_store_dword v164, v129, s[14:15]
	s_mov_b64 exec, -1
	s_add_u32 s14, s8, 0x7000000
	s_addc_u32 s15, s9, 0
	global_load_dwordx4 v[96:99], v162, s[14:15] nt
	global_load_dwordx4 v[100:103], v162, s[14:15] offset:1024 nt
	global_load_dwordx4 v[104:107], v162, s[14:15] offset:2048 nt
	global_load_dwordx4 v[108:111], v162, s[14:15] offset:3072 nt
	s_waitcnt vmcnt(63)
; __device__ __forceinline__ unsigned cvt_pk_bf16(float lo, float hi) { unsigned r; asm volatile("v_cvt_pk_bf16_f32 %0, %1, %2" : "=v"(r) : "v"(lo), "v"(hi)); return r; }
; __device__ void phase_prologue(KP P, LAS unsigned char* lds) {
;     ...
;     for (int row = gw; row < MTOK; row += nw) { float s = 0.f;
; #pragma unroll
;         for (int i = 0; i < 4; ++i) { const int col = lane * 4 + 256 * i; const f32x4 v = __builtin_nontemporal_load((const f32x4*)(P->x + (size_t)row * 1024 + col));
;             s += v.x * v.x + v.y * v.y + v.z * v.z + v.w * v.w; u32x2 w; w.x = cvt_pk_bf16(v.x, v.y); w.y = cvt_pk_bf16(v.z, v.w); *(u32x2*)(xb + (size_t)row * 1024 + col) = w; }
; #pragma unroll
;         for (int d = 32; d >= 1; d >>= 1) s += __shfl_xor(s, d);
;         if (lane == 0) ssq[row] = s; }
	s_add_u32 s16, s10, 0x1c00000
	s_addc_u32 s17, s11, 0
	v_mul_f32_e32 v128, v113, v113
	v_fmac_f32_e32 v128, v112, v112
	v_fmac_f32_e32 v128, v114, v114
	v_fmac_f32_e32 v128, v115, v115
	v_mul_f32_e32 v129, v117, v117
	v_fmac_f32_e32 v129, v116, v116
	v_fmac_f32_e32 v129, v118, v118
	v_fmac_f32_e32 v129, v119, v119
	v_mul_f32_e32 v130, v121, v121
	v_fmac_f32_e32 v130, v120, v120
	v_fmac_f32_e32 v130, v122, v122
	v_fmac_f32_e32 v130, v123, v123
	v_mul_f32_e32 v131, v125, v125
	v_fmac_f32_e32 v131, v124, v124
	v_fmac_f32_e32 v131, v126, v126
	v_fmac_f32_e32 v131, v127, v127
	v_add_f32_e32 v128, v128, v129
	v_add_f32_e32 v128, v128, v130
	v_add_f32_e32 v128, v128, v131
	v_cvt_pk_bf16_f32 v132, v112, v113
	v_cvt_pk_bf16_f32 v133, v114, v115
	v_cvt_pk_bf16_f32 v134, v116, v117
	v_cvt_pk_bf16_f32 v135, v118, v119
	v_cvt_pk_bf16_f32 v136, v120, v121
	v_cvt_pk_bf16_f32 v137, v122, v123
	v_cvt_pk_bf16_f32 v138, v124, v125
	v_cvt_pk_bf16_f32 v139, v126, v127
	global_store_dwordx2 v163, v[132:133], s[16:17]
	global_store_dwordx2 v163, v[134:135], s[16:17] offset:512
	global_store_dwordx2 v163, v[136:137], s[16:17] offset:1024
	global_store_dwordx2 v163, v[138:139], s[16:17] offset:1536
	v_add_f32_dpp v128, v128, v128 quad_perm:[1,0,3,2] row_mask:0xf bank_mask:0xf
	s_nop 1
	v_add_f32_dpp v128, v128, v128 quad_perm:[2,3,0,1] row_mask:0xf bank_mask:0xf
	s_nop 1
	v_add_f32_dpp v128, v128, v128 row_half_mirror row_mask:0xf bank_mask:0xf
	s_nop 1
	v_add_f32_dpp v128, v128, v128 row_mirror row_mask:0xf bank_mask:0xf
	s_nop 1
	v_add_f32_dpp v128, v128, v128 row_bcast:15 row_mask:0xa bank_mask:0xf
	s_nop 1
	v_add_f32_dpp v128, v128, v128 row_bcast:31 row_mask:0xc bank_mask:0xf
	s_nop 1
	v_readlane_b32 s1, v128, 63
	s_add_u32 s14, s12, 0xe000
	s_addc_u32 s15, s13, 0
	s_mov_b64 exec, 1
	v_mov_b32_e32 v129, s1
	global_store_dword v164, v129, s[14:15]
	s_mov_b64 exec, -1
	s_add_u32 s14, s8, 0x7800000
	s_addc_u32 s15, s9, 0
	global_load_dwordx4 v[112:115], v162, s[14:15] nt
	global_load_dwordx4 v[116:119], v162, s[14:15] offset:1024 nt
	global_load_dwordx4 v[120:123], v162, s[14:15] offset:2048 nt
	global_load_dwordx4 v[124:127], v162, s[14:15] offset:3072 nt
	s_waitcnt vmcnt(63)
	s_add_u32 s16, s10, 0x2000000
	s_addc_u32 s17, s11, 0
	v_mul_f32_e32 v128, v1, v1
	v_fmac_f32_e32 v128, v0, v0
	v_fmac_f32_e32 v128, v2, v2
	v_fmac_f32_e32 v128, v3, v3
	v_mul_f32_e32 v129, v5, v5
	v_fmac_f32_e32 v129, v4, v4
	v_fmac_f32_e32 v129, v6, v6
	v_fmac_f32_e32 v129, v7, v7
	v_mul_f32_e32 v130, v9, v9
	v_fmac_f32_e32 v130, v8, v8
	v_fmac_f32_e32 v130, v10, v10
	v_fmac_f32_e32 v130, v11, v11
	v_mul_f32_e32 v131, v13, v13
	v_fmac_f32_e32 v131, v12, v12
	v_fmac_f32_e32 v131, v14, v14
	v_fmac_f32_e32 v131, v15, v15
	v_add_f32_e32 v128, v128, v129
	v_add_f32_e32 v128, v128, v130
	v_add_f32_e32 v128, v128, v131
	v_cvt_pk_bf16_f32 v132, v0, v1
	v_cvt_pk_bf16_f32 v133, v2, v3
	v_cvt_pk_bf16_f32 v134, v4, v5
	v_cvt_pk_bf16_f32 v135, v6, v7
	v_cvt_pk_bf16_f32 v136, v8, v9
	v_cvt_pk_bf16_f32 v137, v10, v11
	v_cvt_pk_bf16_f32 v138, v12, v13
	v_cvt_pk_bf16_f32 v139, v14, v15
	global_store_dwordx2 v163, v[132:133], s[16:17]
	global_store_dwordx2 v163, v[134:135], s[16:17] offset:512
	global_store_dwordx2 v163, v[136:137], s[16:17] offset:1024
	global_store_dwordx2 v163, v[138:139], s[16:17] offset:1536
	v_add_f32_dpp v128, v128, v128 quad_perm:[1,0,3,2] row_mask:0xf bank_mask:0xf
	s_nop 1
	v_add_f32_dpp v128, v128, v128 quad_perm:[2,3,0,1] row_mask:0xf bank_mask:0xf
	s_nop 1
	v_add_f32_dpp v128, v128, v128 row_half_mirror row_mask:0xf bank_mask:0xf
	s_nop 1
	v_add_f32_dpp v128, v128, v128 row_mirror row_mask:0xf bank_mask:0xf
	s_nop 1
	v_add_f32_dpp v128, v128, v128 row_bcast:15 row_mask:0xa bank_mask:0xf
	s_nop 1
	v_add_f32_dpp v128, v128, v128 row_bcast:31 row_mask:0xc bank_mask:0xf
	s_nop 1
	v_readlane_b32 s1, v128, 63
	s_add_u32 s14, s12, 0x10000
	s_addc_u32 s15, s13, 0
	s_mov_b64 exec, 1
	v_mov_b32_e32 v129, s1
	global_store_dword v164, v129, s[14:15]
	s_mov_b64 exec, -1
	s_waitcnt vmcnt(59)
	s_add_u32 s16, s10, 0x2400000
	s_addc_u32 s17, s11, 0
	v_mul_f32_e32 v128, v17, v17
	v_fmac_f32_e32 v128, v16, v16
	v_fmac_f32_e32 v128, v18, v18
	v_fmac_f32_e32 v128, v19, v19
	v_mul_f32_e32 v129, v21, v21
	v_fmac_f32_e32 v129, v20, v20
	v_fmac_f32_e32 v129, v22, v22
	v_fmac_f32_e32 v129, v23, v23
	v_mul_f32_e32 v130, v25, v25
	v_fmac_f32_e32 v130, v24, v24
	v_fmac_f32_e32 v130, v26, v26
	v_fmac_f32_e32 v130, v27, v27
	v_mul_f32_e32 v131, v29, v29
	v_fmac_f32_e32 v131, v28, v28
	v_fmac_f32_e32 v131, v30, v30
	v_fmac_f32_e32 v131, v31, v31
	v_add_f32_e32 v128, v128, v129
	v_add_f32_e32 v128, v128, v130
	v_add_f32_e32 v128, v128, v131
	v_cvt_pk_bf16_f32 v132, v16, v17
	v_cvt_pk_bf16_f32 v133, v18, v19
	v_cvt_pk_bf16_f32 v134, v20, v21
	v_cvt_pk_bf16_f32 v135, v22, v23
	v_cvt_pk_bf16_f32 v136, v24, v25
	v_cvt_pk_bf16_f32 v137, v26, v27
	v_cvt_pk_bf16_f32 v138, v28, v29
	v_cvt_pk_bf16_f32 v139, v30, v31
	global_store_dwordx2 v163, v[132:133], s[16:17]
	global_store_dwordx2 v163, v[134:135], s[16:17] offset:512
	global_store_dwordx2 v163, v[136:137], s[16:17] offset:1024
	global_store_dwordx2 v163, v[138:139], s[16:17] offset:1536
	v_add_f32_dpp v128, v128, v128 quad_perm:[1,0,3,2] row_mask:0xf bank_mask:0xf
	s_nop 1
	v_add_f32_dpp v128, v128, v128 quad_perm:[2,3,0,1] row_mask:0xf bank_mask:0xf
	s_nop 1
	v_add_f32_dpp v128, v128, v128 row_half_mirror row_mask:0xf bank_mask:0xf
	s_nop 1
	v_add_f32_dpp v128, v128, v128 row_mirror row_mask:0xf bank_mask:0xf
	s_nop 1
	v_add_f32_dpp v128, v128, v128 row_bcast:15 row_mask:0xa bank_mask:0xf
	s_nop 1
	v_add_f32_dpp v128, v128, v128 row_bcast:31 row_mask:0xc bank_mask:0xf
	s_nop 1
	v_readlane_b32 s1, v128, 63
	s_add_u32 s14, s12, 0x12000
	s_addc_u32 s15, s13, 0
	s_mov_b64 exec, 1
	v_mov_b32_e32 v129, s1
	global_store_dword v164, v129, s[14:15]
	s_mov_b64 exec, -1
	s_waitcnt vmcnt(55)
; __device__ __forceinline__ unsigned cvt_pk_bf16(float lo, float hi) { unsigned r; asm volatile("v_cvt_pk_bf16_f32 %0, %1, %2" : "=v"(r) : "v"(lo), "v"(hi)); return r; }
; __device__ void phase_prologue(KP P, LAS unsigned char* lds) {
;     ...
;     for (int row = gw; row < MTOK; row += nw) { float s = 0.f;
; #pragma unroll
;         for (int i = 0; i < 4; ++i) { const int col = lane * 4 + 256 * i; const f32x4 v = __builtin_nontemporal_load((const f32x4*)(P->x + (size_t)row * 1024 + col));
;             s += v.x * v.x + v.y * v.y + v.z * v.z + v.w * v.w; u32x2 w; w.x = cvt_pk_bf16(v.x, v.y); w.y = cvt_pk_bf16(v.z, v.w); *(u32x2*)(xb + (size_t)row * 1024 + col) = w; }
; #pragma unroll
;         for (int d = 32; d >= 1; d >>= 1) s += __shfl_xor(s, d);
;         if (lane == 0) ssq[row] = s; }
	s_add_u32 s16, s10, 0x2800000
	s_addc_u32 s17, s11, 0
	v_mul_f32_e32 v128, v33, v33
	v_fmac_f32_e32 v128, v32, v32
	v_fmac_f32_e32 v128, v34, v34
	v_fmac_f32_e32 v128, v35, v35
	v_mul_f32_e32 v129, v37, v37
	v_fmac_f32_e32 v129, v36, v36
	v_fmac_f32_e32 v129, v38, v38
	v_fmac_f32_e32 v129, v39, v39
	v_mul_f32_e32 v130, v41, v41
	v_fmac_f32_e32 v130, v40, v40
	v_fmac_f32_e32 v130, v42, v42
	v_fmac_f32_e32 v130, v43, v43
	v_mul_f32_e32 v131, v45, v45
	v_fmac_f32_e32 v131, v44, v44
	v_fmac_f32_e32 v131, v46, v46
	v_fmac_f32_e32 v131, v47, v47
	v_add_f32_e32 v128, v128, v129
	v_add_f32_e32 v128, v128, v130
	v_add_f32_e32 v128, v128, v131
	v_cvt_pk_bf16_f32 v132, v32, v33
	v_cvt_pk_bf16_f32 v133, v34, v35
	v_cvt_pk_bf16_f32 v134, v36, v37
	v_cvt_pk_bf16_f32 v135, v38, v39
	v_cvt_pk_bf16_f32 v136, v40, v41
	v_cvt_pk_bf16_f32 v137, v42, v43
	v_cvt_pk_bf16_f32 v138, v44, v45
	v_cvt_pk_bf16_f32 v139, v46, v47
	global_store_dwordx2 v163, v[132:133], s[16:17]
	global_store_dwordx2 v163, v[134:135], s[16:17] offset:512
	global_store_dwordx2 v163, v[136:137], s[16:17] offset:1024
	global_store_dwordx2 v163, v[138:139], s[16:17] offset:1536
	v_add_f32_dpp v128, v128, v128 quad_perm:[1,0,3,2] row_mask:0xf bank_mask:0xf
	s_nop 1
	v_add_f32_dpp v128, v128, v128 quad_perm:[2,3,0,1] row_mask:0xf bank_mask:0xf
	s_nop 1
	v_add_f32_dpp v128, v128, v128 row_half_mirror row_mask:0xf bank_mask:0xf
	s_nop 1
	v_add_f32_dpp v128, v128, v128 row_mirror row_mask:0xf bank_mask:0xf
	s_nop 1
	v_add_f32_dpp v128, v128, v128 row_bcast:15 row_mask:0xa bank_mask:0xf
	s_nop 1
	v_add_f32_dpp v128, v128, v128 row_bcast:31 row_mask:0xc bank_mask:0xf
	s_nop 1
	v_readlane_b32 s1, v128, 63
	s_add_u32 s14, s12, 0x14000
	s_addc_u32 s15, s13, 0
	s_mov_b64 exec, 1
	v_mov_b32_e32 v129, s1
	global_store_dword v164, v129, s[14:15]
	s_mov_b64 exec, -1
	s_waitcnt vmcnt(51)
	s_add_u32 s16, s10, 0x2c00000
	s_addc_u32 s17, s11, 0
	v_mul_f32_e32 v128, v49, v49
	v_fmac_f32_e32 v128, v48, v48
	v_fmac_f32_e32 v128, v50, v50
	v_fmac_f32_e32 v128, v51, v51
	v_mul_f32_e32 v129, v53, v53
	v_fmac_f32_e32 v129, v52, v52
	v_fmac_f32_e32 v129, v54, v54
	v_fmac_f32_e32 v129, v55, v55
	v_mul_f32_e32 v130, v57, v57
	v_fmac_f32_e32 v130, v56, v56
	v_fmac_f32_e32 v130, v58, v58
	v_fmac_f32_e32 v130, v59, v59
	v_mul_f32_e32 v131, v61, v61
	v_fmac_f32_e32 v131, v60, v60
	v_fmac_f32_e32 v131, v62, v62
	v_fmac_f32_e32 v131, v63, v63
	v_add_f32_e32 v128, v128, v129
	v_add_f32_e32 v128, v128, v130
	v_add_f32_e32 v128, v128, v131
	v_cvt_pk_bf16_f32 v132, v48, v49
	v_cvt_pk_bf16_f32 v133, v50, v51
	v_cvt_pk_bf16_f32 v134, v52, v53
	v_cvt_pk_bf16_f32 v135, v54, v55
	v_cvt_pk_bf16_f32 v136, v56, v57
	v_cvt_pk_bf16_f32 v137, v58, v59
	v_cvt_pk_bf16_f32 v138, v60, v61
	v_cvt_pk_bf16_f32 v139, v62, v63
	global_store_dwordx2 v163, v[132:133], s[16:17]
	global_store_dwordx2 v163, v[134:135], s[16:17] offset:512
	global_store_dwordx2 v163, v[136:137], s[16:17] offset:1024
	global_store_dwordx2 v163, v[138:139], s[16:17] offset:1536
	v_add_f32_dpp v128, v128, v128 quad_perm:[1,0,3,2] row_mask:0xf bank_mask:0xf
	s_nop 1
	v_add_f32_dpp v128, v128, v128 quad_perm:[2,3,0,1] row_mask:0xf bank_mask:0xf
	s_nop 1
	v_add_f32_dpp v128, v128, v128 row_half_mirror row_mask:0xf bank_mask:0xf
	s_nop 1
	v_add_f32_dpp v128, v128, v128 row_mirror row_mask:0xf bank_mask:0xf
	s_nop 1
	v_add_f32_dpp v128, v128, v128 row_bcast:15 row_mask:0xa bank_mask:0xf
	s_nop 1
	v_add_f32_dpp v128, v128, v128 row_bcast:31 row_mask:0xc bank_mask:0xf
	s_nop 1
	v_readlane_b32 s1, v128, 63
	s_add_u32 s14, s12, 0x16000
	s_addc_u32 s15, s13, 0
	s_mov_b64 exec, 1
	v_mov_b32_e32 v129, s1
	global_store_dword v164, v129, s[14:15]
	s_mov_b64 exec, -1
	s_waitcnt vmcnt(47)
	s_add_u32 s16, s10, 0x3000000
	s_addc_u32 s17, s11, 0
	v_mul_f32_e32 v128, v65, v65
	v_fmac_f32_e32 v128, v64, v64
	v_fmac_f32_e32 v128, v66, v66
	v_fmac_f32_e32 v128, v67, v67
	v_mul_f32_e32 v129, v69, v69
	v_fmac_f32_e32 v129, v68, v68
	v_fmac_f32_e32 v129, v70, v70
	v_fmac_f32_e32 v129, v71, v71
	v_mul_f32_e32 v130, v73, v73
	v_fmac_f32_e32 v130, v72, v72
	v_fmac_f32_e32 v130, v74, v74
	v_fmac_f32_e32 v130, v75, v75
	v_mul_f32_e32 v131, v77, v77
	v_fmac_f32_e32 v131, v76, v76
	v_fmac_f32_e32 v131, v78, v78
	v_fmac_f32_e32 v131, v79, v79
	v_add_f32_e32 v128, v128, v129
	v_add_f32_e32 v128, v128, v130
	v_add_f32_e32 v128, v128, v131
	v_cvt_pk_bf16_f32 v132, v64, v65
	v_cvt_pk_bf16_f32 v133, v66, v67
	v_cvt_pk_bf16_f32 v134, v68, v69
	v_cvt_pk_bf16_f32 v135, v70, v71
	v_cvt_pk_bf16_f32 v136, v72, v73
	v_cvt_pk_bf16_f32 v137, v74, v75
	v_cvt_pk_bf16_f32 v138, v76, v77
	v_cvt_pk_bf16_f32 v139, v78, v79
	global_store_dwordx2 v163, v[132:133], s[16:17]
	global_store_dwordx2 v163, v[134:135], s[16:17] offset:512
	global_store_dwordx2 v163, v[136:137], s[16:17] offset:1024
	global_store_dwordx2 v163, v[138:139], s[16:17] offset:1536
	v_add_f32_dpp v128, v128, v128 quad_perm:[1,0,3,2] row_mask:0xf bank_mask:0xf
	s_nop 1
	v_add_f32_dpp v128, v128, v128 quad_perm:[2,3,0,1] row_mask:0xf bank_mask:0xf
	s_nop 1
	v_add_f32_dpp v128, v128, v128 row_half_mirror row_mask:0xf bank_mask:0xf
	s_nop 1
	v_add_f32_dpp v128, v128, v128 row_mirror row_mask:0xf bank_mask:0xf
	s_nop 1
	v_add_f32_dpp v128, v128, v128 row_bcast:15 row_mask:0xa bank_mask:0xf
	s_nop 1
	v_add_f32_dpp v128, v128, v128 row_bcast:31 row_mask:0xc bank_mask:0xf
	s_nop 1
	v_readlane_b32 s1, v128, 63
	s_add_u32 s14, s12, 0x18000
	s_addc_u32 s15, s13, 0
	s_mov_b64 exec, 1
	v_mov_b32_e32 v129, s1
	global_store_dword v164, v129, s[14:15]
	s_mov_b64 exec, -1
	s_waitcnt vmcnt(43)
; __device__ __forceinline__ unsigned cvt_pk_bf16(float lo, float hi) { unsigned r; asm volatile("v_cvt_pk_bf16_f32 %0, %1, %2" : "=v"(r) : "v"(lo), "v"(hi)); return r; }
; __device__ void phase_prologue(KP P, LAS unsigned char* lds) {
;     ...
;     for (int row = gw; row < MTOK; row += nw) { float s = 0.f;
; #pragma unroll
;         for (int i = 0; i < 4; ++i) { const int col = lane * 4 + 256 * i; const f32x4 v = __builtin_nontemporal_load((const f32x4*)(P->x + (size_t)row * 1024 + col));
;             s += v.x * v.x + v.y * v.y + v.z * v.z + v.w * v.w; u32x2 w; w.x = cvt_pk_bf16(v.x, v.y); w.y = cvt_pk_bf16(v.z, v.w); *(u32x2*)(xb + (size_t)row * 1024 + col) = w; }
; #pragma unroll
;         for (int d = 32; d >= 1; d >>= 1) s += __shfl_xor(s, d);
;         if (lane == 0) ssq[row] = s; }
	s_add_u32 s16, s10, 0x3400000
	s_addc_u32 s17, s11, 0
	v_mul_f32_e32 v128, v81, v81
	v_fmac_f32_e32 v128, v80, v80
	v_fmac_f32_e32 v128, v82, v82
	v_fmac_f32_e32 v128, v83, v83
	v_mul_f32_e32 v129, v85, v85
	v_fmac_f32_e32 v129, v84, v84
	v_fmac_f32_e32 v129, v86, v86
	v_fmac_f32_e32 v129, v87, v87
	v_mul_f32_e32 v130, v89, v89
	v_fmac_f32_e32 v130, v88, v88
	v_fmac_f32_e32 v130, v90, v90
	v_fmac_f32_e32 v130, v91, v91
	v_mul_f32_e32 v131, v93, v93
	v_fmac_f32_e32 v131, v92, v92
	v_fmac_f32_e32 v131, v94, v94
	v_fmac_f32_e32 v131, v95, v95
	v_add_f32_e32 v128, v128, v129
	v_add_f32_e32 v128, v128, v130
	v_add_f32_e32 v128, v128, v131
	v_cvt_pk_bf16_f32 v132, v80, v81
	v_cvt_pk_bf16_f32 v133, v82, v83
	v_cvt_pk_bf16_f32 v134, v84, v85
	v_cvt_pk_bf16_f32 v135, v86, v87
	v_cvt_pk_bf16_f32 v136, v88, v89
	v_cvt_pk_bf16_f32 v137, v90, v91
	v_cvt_pk_bf16_f32 v138, v92, v93
	v_cvt_pk_bf16_f32 v139, v94, v95
	global_store_dwordx2 v163, v[132:133], s[16:17]
	global_store_dwordx2 v163, v[134:135], s[16:17] offset:512
	global_store_dwordx2 v163, v[136:137], s[16:17] offset:1024
	global_store_dwordx2 v163, v[138:139], s[16:17] offset:1536
	v_add_f32_dpp v128, v128, v128 quad_perm:[1,0,3,2] row_mask:0xf bank_mask:0xf
	s_nop 1
	v_add_f32_dpp v128, v128, v128 quad_perm:[2,3,0,1] row_mask:0xf bank_mask:0xf
	s_nop 1
	v_add_f32_dpp v128, v128, v128 row_half_mirror row_mask:0xf bank_mask:0xf
	s_nop 1
	v_add_f32_dpp v128, v128, v128 row_mirror row_mask:0xf bank_mask:0xf
	s_nop 1
	v_add_f32_dpp v128, v128, v128 row_bcast:15 row_mask:0xa bank_mask:0xf
	s_nop 1
	v_add_f32_dpp v128, v128, v128 row_bcast:31 row_mask:0xc bank_mask:0xf
	s_nop 1
	v_readlane_b32 s1, v128, 63
	s_add_u32 s14, s12, 0x1a000
	s_addc_u32 s15, s13, 0
	s_mov_b64 exec, 1
	v_mov_b32_e32 v129, s1
	global_store_dword v164, v129, s[14:15]
	s_mov_b64 exec, -1
	s_waitcnt vmcnt(39)
	s_add_u32 s16, s10, 0x3800000
	s_addc_u32 s17, s11, 0
	v_mul_f32_e32 v128, v97, v97
	v_fmac_f32_e32 v128, v96, v96
	v_fmac_f32_e32 v128, v98, v98
	v_fmac_f32_e32 v128, v99, v99
	v_mul_f32_e32 v129, v101, v101
	v_fmac_f32_e32 v129, v100, v100
	v_fmac_f32_e32 v129, v102, v102
	v_fmac_f32_e32 v129, v103, v103
	v_mul_f32_e32 v130, v105, v105
	v_fmac_f32_e32 v130, v104, v104
	v_fmac_f32_e32 v130, v106, v106
	v_fmac_f32_e32 v130, v107, v107
	v_mul_f32_e32 v131, v109, v109
	v_fmac_f32_e32 v131, v108, v108
	v_fmac_f32_e32 v131, v110, v110
	v_fmac_f32_e32 v131, v111, v111
	v_add_f32_e32 v128, v128, v129
	v_add_f32_e32 v128, v128, v130
	v_add_f32_e32 v128, v128, v131
	v_cvt_pk_bf16_f32 v132, v96, v97
	v_cvt_pk_bf16_f32 v133, v98, v99
	v_cvt_pk_bf16_f32 v134, v100, v101
	v_cvt_pk_bf16_f32 v135, v102, v103
	v_cvt_pk_bf16_f32 v136, v104, v105
	v_cvt_pk_bf16_f32 v137, v106, v107
	v_cvt_pk_bf16_f32 v138, v108, v109
	v_cvt_pk_bf16_f32 v139, v110, v111
	global_store_dwordx2 v163, v[132:133], s[16:17]
	global_store_dwordx2 v163, v[134:135], s[16:17] offset:512
	global_store_dwordx2 v163, v[136:137], s[16:17] offset:1024
	global_store_dwordx2 v163, v[138:139], s[16:17] offset:1536
	v_add_f32_dpp v128, v128, v128 quad_perm:[1,0,3,2] row_mask:0xf bank_mask:0xf
	s_nop 1
	v_add_f32_dpp v128, v128, v128 quad_perm:[2,3,0,1] row_mask:0xf bank_mask:0xf
	s_nop 1
	v_add_f32_dpp v128, v128, v128 row_half_mirror row_mask:0xf bank_mask:0xf
	s_nop 1
	v_add_f32_dpp v128, v128, v128 row_mirror row_mask:0xf bank_mask:0xf
	s_nop 1
	v_add_f32_dpp v128, v128, v128 row_bcast:15 row_mask:0xa bank_mask:0xf
	s_nop 1
	v_add_f32_dpp v128, v128, v128 row_bcast:31 row_mask:0xc bank_mask:0xf
	s_nop 1
	v_readlane_b32 s1, v128, 63
	s_add_u32 s14, s12, 0x1c000
	s_addc_u32 s15, s13, 0
	s_mov_b64 exec, 1
	v_mov_b32_e32 v129, s1
	global_store_dword v164, v129, s[14:15]
	s_mov_b64 exec, -1
	s_waitcnt vmcnt(35)
	s_add_u32 s16, s10, 0x3c00000
	s_addc_u32 s17, s11, 0
	v_mul_f32_e32 v128, v113, v113
	v_fmac_f32_e32 v128, v112, v112
	v_fmac_f32_e32 v128, v114, v114
	v_fmac_f32_e32 v128, v115, v115
	v_mul_f32_e32 v129, v117, v117
	v_fmac_f32_e32 v129, v116, v116
	v_fmac_f32_e32 v129, v118, v118
	v_fmac_f32_e32 v129, v119, v119
	v_mul_f32_e32 v130, v121, v121
	v_fmac_f32_e32 v130, v120, v120
	v_fmac_f32_e32 v130, v122, v122
	v_fmac_f32_e32 v130, v123, v123
	v_mul_f32_e32 v131, v125, v125
	v_fmac_f32_e32 v131, v124, v124
	v_fmac_f32_e32 v131, v126, v126
	v_fmac_f32_e32 v131, v127, v127
	v_add_f32_e32 v128, v128, v129
	v_add_f32_e32 v128, v128, v130
	v_add_f32_e32 v128, v128, v131
	v_cvt_pk_bf16_f32 v132, v112, v113
	v_cvt_pk_bf16_f32 v133, v114, v115
	v_cvt_pk_bf16_f32 v134, v116, v117
	v_cvt_pk_bf16_f32 v135, v118, v119
	v_cvt_pk_bf16_f32 v136, v120, v121
	v_cvt_pk_bf16_f32 v137, v122, v123
	v_cvt_pk_bf16_f32 v138, v124, v125
	v_cvt_pk_bf16_f32 v139, v126, v127
	global_store_dwordx2 v163, v[132:133], s[16:17]
	global_store_dwordx2 v163, v[134:135], s[16:17] offset:512
	global_store_dwordx2 v163, v[136:137], s[16:17] offset:1024
	global_store_dwordx2 v163, v[138:139], s[16:17] offset:1536
	v_add_f32_dpp v128, v128, v128 quad_perm:[1,0,3,2] row_mask:0xf bank_mask:0xf
	s_nop 1
	v_add_f32_dpp v128, v128, v128 quad_perm:[2,3,0,1] row_mask:0xf bank_mask:0xf
	s_nop 1
	v_add_f32_dpp v128, v128, v128 row_half_mirror row_mask:0xf bank_mask:0xf
	s_nop 1
	v_add_f32_dpp v128, v128, v128 row_mirror row_mask:0xf bank_mask:0xf
	s_nop 1
	v_add_f32_dpp v128, v128, v128 row_bcast:15 row_mask:0xa bank_mask:0xf
	s_nop 1
	v_add_f32_dpp v128, v128, v128 row_bcast:31 row_mask:0xc bank_mask:0xf
	s_nop 1
	v_readlane_b32 s1, v128, 63
	s_add_u32 s14, s12, 0x1e000
	s_addc_u32 s15, s13, 0
	s_mov_b64 exec, 1
	v_mov_b32_e32 v129, s1
	global_store_dword v164, v129, s[14:15]
	s_mov_b64 exec, -1
; __device__ __forceinline__ unsigned cvt_pk_bf16(float lo, float hi) { unsigned r; asm volatile("v_cvt_pk_bf16_f32 %0, %1, %2" : "=v"(r) : "v"(lo), "v"(hi)); return r; }
; __device__ void phase_prologue(KP P, LAS unsigned char* lds) {
;     ...
;     bf16_t* pb = (bf16_t*)(ws + OFF_PB);
; #pragma unroll 16
;     for (size_t i = (size_t)blockIdx.x * 512 + tid; i < (size_t)2 * MTOK * 256 / 4; i += (size_t)nw * 64) {
;         const f32x4 v = __builtin_nontemporal_load((const f32x4*)(P->p + i * 4)); u32x2 w; w.x = cvt_pk_bf16(v.x, v.y); w.y = cvt_pk_bf16(v.z, v.w); *(u32x2*)(pb + i * 4) = w; }
	v_lshl_add_u32 v160, s2, 9, v208
	v_lshlrev_b32_e32 v161, 4, v160
	v_lshlrev_b32_e32 v160, 3, v160
	s_add_u32 s10, s90, 0x2700000
	s_addc_u32 s11, s91, 0
	s_add_u32 s14, s18, 0x0
	s_addc_u32 s15, s19, 0
	global_load_dwordx4 v[0:3], v161, s[14:15] nt
	s_add_u32 s14, s18, 0x200000
	s_addc_u32 s15, s19, 0
	global_load_dwordx4 v[4:7], v161, s[14:15] nt
	s_add_u32 s14, s18, 0x400000
	s_addc_u32 s15, s19, 0
	global_load_dwordx4 v[8:11], v161, s[14:15] nt
	s_add_u32 s14, s18, 0x600000
	s_addc_u32 s15, s19, 0
	global_load_dwordx4 v[12:15], v161, s[14:15] nt
	s_add_u32 s14, s18, 0x800000
	s_addc_u32 s15, s19, 0
	global_load_dwordx4 v[16:19], v161, s[14:15] nt
	s_add_u32 s14, s18, 0xa00000
	s_addc_u32 s15, s19, 0
	global_load_dwordx4 v[20:23], v161, s[14:15] nt
	s_add_u32 s14, s18, 0xc00000
	s_addc_u32 s15, s19, 0
	global_load_dwordx4 v[24:27], v161, s[14:15] nt
	s_add_u32 s14, s18, 0xe00000
	s_addc_u32 s15, s19, 0
	global_load_dwordx4 v[28:31], v161, s[14:15] nt
	s_add_u32 s14, s18, 0x1000000
	s_addc_u32 s15, s19, 0
	global_load_dwordx4 v[32:35], v161, s[14:15] nt
	s_add_u32 s14, s18, 0x1200000
	s_addc_u32 s15, s19, 0
	global_load_dwordx4 v[36:39], v161, s[14:15] nt
	s_add_u32 s14, s18, 0x1400000
	s_addc_u32 s15, s19, 0
	global_load_dwordx4 v[40:43], v161, s[14:15] nt
	s_add_u32 s14, s18, 0x1600000
	s_addc_u32 s15, s19, 0
	global_load_dwordx4 v[44:47], v161, s[14:15] nt
	s_add_u32 s14, s18, 0x1800000
	s_addc_u32 s15, s19, 0
	global_load_dwordx4 v[48:51], v161, s[14:15] nt
	s_add_u32 s14, s18, 0x1a00000
	s_addc_u32 s15, s19, 0
	global_load_dwordx4 v[52:55], v161, s[14:15] nt
	s_add_u32 s14, s18, 0x1c00000
	s_addc_u32 s15, s19, 0
	global_load_dwordx4 v[56:59], v161, s[14:15] nt
	s_add_u32 s14, s18, 0x1e00000
	s_addc_u32 s15, s19, 0
	global_load_dwordx4 v[60:63], v161, s[14:15] nt
	s_add_u32 s14, s18, 0x2000000
	s_addc_u32 s15, s19, 0
	global_load_dwordx4 v[64:67], v161, s[14:15] nt
	s_add_u32 s14, s18, 0x2200000
	s_addc_u32 s15, s19, 0
	global_load_dwordx4 v[68:71], v161, s[14:15] nt
	s_add_u32 s14, s18, 0x2400000
	s_addc_u32 s15, s19, 0
	global_load_dwordx4 v[72:75], v161, s[14:15] nt
	s_add_u32 s14, s18, 0x2600000
	s_addc_u32 s15, s19, 0
	global_load_dwordx4 v[76:79], v161, s[14:15] nt
	s_add_u32 s14, s18, 0x2800000
	s_addc_u32 s15, s19, 0
	global_load_dwordx4 v[80:83], v161, s[14:15] nt
	s_add_u32 s14, s18, 0x2a00000
	s_addc_u32 s15, s19, 0
	global_load_dwordx4 v[84:87], v161, s[14:15] nt
	s_add_u32 s14, s18, 0x2c00000
	s_addc_u32 s15, s19, 0
	global_load_dwordx4 v[88:91], v161, s[14:15] nt
	s_add_u32 s14, s18, 0x2e00000
	s_addc_u32 s15, s19, 0
	global_load_dwordx4 v[92:95], v161, s[14:15] nt
	s_add_u32 s14, s18, 0x3000000
	s_addc_u32 s15, s19, 0
	global_load_dwordx4 v[96:99], v161, s[14:15] nt
	s_add_u32 s14, s18, 0x3200000
	s_addc_u32 s15, s19, 0
	global_load_dwordx4 v[100:103], v161, s[14:15] nt
	s_add_u32 s14, s18, 0x3400000
	s_addc_u32 s15, s19, 0
	global_load_dwordx4 v[104:107], v161, s[14:15] nt
	s_add_u32 s14, s18, 0x3600000
	s_addc_u32 s15, s19, 0
	global_load_dwordx4 v[108:111], v161, s[14:15] nt
	s_add_u32 s14, s18, 0x3800000
	s_addc_u32 s15, s19, 0
	global_load_dwordx4 v[112:115], v161, s[14:15] nt
	s_add_u32 s14, s18, 0x3a00000
	s_addc_u32 s15, s19, 0
	global_load_dwordx4 v[116:119], v161, s[14:15] nt
	s_add_u32 s14, s18, 0x3c00000
	s_addc_u32 s15, s19, 0
	global_load_dwordx4 v[120:123], v161, s[14:15] nt
	s_add_u32 s14, s18, 0x3e00000
	s_addc_u32 s15, s19, 0
	global_load_dwordx4 v[124:127], v161, s[14:15] nt
	s_waitcnt vmcnt(16)
; __device__ __forceinline__ unsigned cvt_pk_bf16(float lo, float hi) { unsigned r; asm volatile("v_cvt_pk_bf16_f32 %0, %1, %2" : "=v"(r) : "v"(lo), "v"(hi)); return r; }
; __device__ void phase_prologue(KP P, LAS unsigned char* lds) {
;     ...
;     bf16_t* pb = (bf16_t*)(ws + OFF_PB);
; #pragma unroll 16
;     for (size_t i = (size_t)blockIdx.x * 512 + tid; i < (size_t)2 * MTOK * 256 / 4; i += (size_t)nw * 64) {
;         const f32x4 v = __builtin_nontemporal_load((const f32x4*)(P->p + i * 4)); u32x2 w; w.x = cvt_pk_bf16(v.x, v.y); w.y = cvt_pk_bf16(v.z, v.w); *(u32x2*)(pb + i * 4) = w; }
	v_cvt_pk_bf16_f32 v0, v0, v1
	v_cvt_pk_bf16_f32 v1, v2, v3
	s_add_u32 s14, s10, 0x0
	s_addc_u32 s15, s11, 0
	global_store_dwordx2 v160, v[0:1], s[14:15]
	v_cvt_pk_bf16_f32 v4, v4, v5
	v_cvt_pk_bf16_f32 v5, v6, v7
	s_add_u32 s14, s10, 0x100000
	s_addc_u32 s15, s11, 0
	global_store_dwordx2 v160, v[4:5], s[14:15]
	v_cvt_pk_bf16_f32 v8, v8, v9
	v_cvt_pk_bf16_f32 v9, v10, v11
	s_add_u32 s14, s10, 0x200000
	s_addc_u32 s15, s11, 0
	global_store_dwordx2 v160, v[8:9], s[14:15]
	v_cvt_pk_bf16_f32 v12, v12, v13
	v_cvt_pk_bf16_f32 v13, v14, v15
	s_add_u32 s14, s10, 0x300000
	s_addc_u32 s15, s11, 0
	global_store_dwordx2 v160, v[12:13], s[14:15]
	v_cvt_pk_bf16_f32 v16, v16, v17
	v_cvt_pk_bf16_f32 v17, v18, v19
	s_add_u32 s14, s10, 0x400000
	s_addc_u32 s15, s11, 0
	global_store_dwordx2 v160, v[16:17], s[14:15]
	v_cvt_pk_bf16_f32 v20, v20, v21
	v_cvt_pk_bf16_f32 v21, v22, v23
	s_add_u32 s14, s10, 0x500000
	s_addc_u32 s15, s11, 0
	global_store_dwordx2 v160, v[20:21], s[14:15]
	v_cvt_pk_bf16_f32 v24, v24, v25
	v_cvt_pk_bf16_f32 v25, v26, v27
	s_add_u32 s14, s10, 0x600000
	s_addc_u32 s15, s11, 0
	global_store_dwordx2 v160, v[24:25], s[14:15]
	v_cvt_pk_bf16_f32 v28, v28, v29
	v_cvt_pk_bf16_f32 v29, v30, v31
	s_add_u32 s14, s10, 0x700000
	s_addc_u32 s15, s11, 0
	global_store_dwordx2 v160, v[28:29], s[14:15]
	v_cvt_pk_bf16_f32 v32, v32, v33
	v_cvt_pk_bf16_f32 v33, v34, v35
	s_add_u32 s14, s10, 0x800000
	s_addc_u32 s15, s11, 0
	global_store_dwordx2 v160, v[32:33], s[14:15]
	v_cvt_pk_bf16_f32 v36, v36, v37
	v_cvt_pk_bf16_f32 v37, v38, v39
	s_add_u32 s14, s10, 0x900000
	s_addc_u32 s15, s11, 0
	global_store_dwordx2 v160, v[36:37], s[14:15]
	v_cvt_pk_bf16_f32 v40, v40, v41
	v_cvt_pk_bf16_f32 v41, v42, v43
	s_add_u32 s14, s10, 0xa00000
	s_addc_u32 s15, s11, 0
	global_store_dwordx2 v160, v[40:41], s[14:15]
	v_cvt_pk_bf16_f32 v44, v44, v45
	v_cvt_pk_bf16_f32 v45, v46, v47
	s_add_u32 s14, s10, 0xb00000
	s_addc_u32 s15, s11, 0
	global_store_dwordx2 v160, v[44:45], s[14:15]
	v_cvt_pk_bf16_f32 v48, v48, v49
	v_cvt_pk_bf16_f32 v49, v50, v51
	s_add_u32 s14, s10, 0xc00000
	s_addc_u32 s15, s11, 0
	global_store_dwordx2 v160, v[48:49], s[14:15]
	v_cvt_pk_bf16_f32 v52, v52, v53
	v_cvt_pk_bf16_f32 v53, v54, v55
	s_add_u32 s14, s10, 0xd00000
	s_addc_u32 s15, s11, 0
	global_store_dwordx2 v160, v[52:53], s[14:15]
	v_cvt_pk_bf16_f32 v56, v56, v57
	v_cvt_pk_bf16_f32 v57, v58, v59
	s_add_u32 s14, s10, 0xe00000
	s_addc_u32 s15, s11, 0
	global_store_dwordx2 v160, v[56:57], s[14:15]
	v_cvt_pk_bf16_f32 v60, v60, v61
	v_cvt_pk_bf16_f32 v61, v62, v63
	s_add_u32 s14, s10, 0xf00000
	s_addc_u32 s15, s11, 0
	global_store_dwordx2 v160, v[60:61], s[14:15]
	s_waitcnt vmcnt(16)
	v_cvt_pk_bf16_f32 v64, v64, v65
	v_cvt_pk_bf16_f32 v65, v66, v67
	s_add_u32 s14, s10, 0x1000000
	s_addc_u32 s15, s11, 0
	global_store_dwordx2 v160, v[64:65], s[14:15]
	v_cvt_pk_bf16_f32 v68, v68, v69
	v_cvt_pk_bf16_f32 v69, v70, v71
	s_add_u32 s14, s10, 0x1100000
	s_addc_u32 s15, s11, 0
	global_store_dwordx2 v160, v[68:69], s[14:15]
	v_cvt_pk_bf16_f32 v72, v72, v73
	v_cvt_pk_bf16_f32 v73, v74, v75
	s_add_u32 s14, s10, 0x1200000
	s_addc_u32 s15, s11, 0
	global_store_dwordx2 v160, v[72:73], s[14:15]
	v_cvt_pk_bf16_f32 v76, v76, v77
	v_cvt_pk_bf16_f32 v77, v78, v79
	s_add_u32 s14, s10, 0x1300000
	s_addc_u32 s15, s11, 0
	global_store_dwordx2 v160, v[76:77], s[14:15]
	v_cvt_pk_bf16_f32 v80, v80, v81
	v_cvt_pk_bf16_f32 v81, v82, v83
	s_add_u32 s14, s10, 0x1400000
	s_addc_u32 s15, s11, 0
	global_store_dwordx2 v160, v[80:81], s[14:15]
	v_cvt_pk_bf16_f32 v84, v84, v85
	v_cvt_pk_bf16_f32 v85, v86, v87
	s_add_u32 s14, s10, 0x1500000
	s_addc_u32 s15, s11, 0
	global_store_dwordx2 v160, v[84:85], s[14:15]
	v_cvt_pk_bf16_f32 v88, v88, v89
	v_cvt_pk_bf16_f32 v89, v90, v91
	s_add_u32 s14, s10, 0x1600000
	s_addc_u32 s15, s11, 0
	global_store_dwordx2 v160, v[88:89], s[14:15]
	v_cvt_pk_bf16_f32 v92, v92, v93
	v_cvt_pk_bf16_f32 v93, v94, v95
	s_add_u32 s14, s10, 0x1700000
	s_addc_u32 s15, s11, 0
	global_store_dwordx2 v160, v[92:93], s[14:15]
	v_cvt_pk_bf16_f32 v96, v96, v97
	v_cvt_pk_bf16_f32 v97, v98, v99
	s_add_u32 s14, s10, 0x1800000
	s_addc_u32 s15, s11, 0
	global_store_dwordx2 v160, v[96:97], s[14:15]
	v_cvt_pk_bf16_f32 v100, v100, v101
	v_cvt_pk_bf16_f32 v101, v102, v103
	s_add_u32 s14, s10, 0x1900000
	s_addc_u32 s15, s11, 0
	global_store_dwordx2 v160, v[100:101], s[14:15]
	v_cvt_pk_bf16_f32 v104, v104, v105
	v_cvt_pk_bf16_f32 v105, v106, v107
	s_add_u32 s14, s10, 0x1a00000
	s_addc_u32 s15, s11, 0
	global_store_dwordx2 v160, v[104:105], s[14:15]
	v_cvt_pk_bf16_f32 v108, v108, v109
	v_cvt_pk_bf16_f32 v109, v110, v111
	s_add_u32 s14, s10, 0x1b00000
	s_addc_u32 s15, s11, 0
	global_store_dwordx2 v160, v[108:109], s[14:15]
	v_cvt_pk_bf16_f32 v112, v112, v113
	v_cvt_pk_bf16_f32 v113, v114, v115
	s_add_u32 s14, s10, 0x1c00000
	s_addc_u32 s15, s11, 0
	global_store_dwordx2 v160, v[112:113], s[14:15]
	v_cvt_pk_bf16_f32 v116, v116, v117
	v_cvt_pk_bf16_f32 v117, v118, v119
	s_add_u32 s14, s10, 0x1d00000
	s_addc_u32 s15, s11, 0
	global_store_dwordx2 v160, v[116:117], s[14:15]
	v_cvt_pk_bf16_f32 v120, v120, v121
	v_cvt_pk_bf16_f32 v121, v122, v123
	s_add_u32 s14, s10, 0x1e00000
	s_addc_u32 s15, s11, 0
	global_store_dwordx2 v160, v[120:121], s[14:15]
	v_cvt_pk_bf16_f32 v124, v124, v125
	v_cvt_pk_bf16_f32 v125, v126, v127
	s_add_u32 s14, s10, 0x1f00000
	s_addc_u32 s15, s11, 0
	global_store_dwordx2 v160, v[124:125], s[14:15]
	s_branch .LBB0_534
.Lpro_generic:
	v_cmp_gt_i32_e32 vcc, s71, v6
	s_and_saveexec_b64 s[6:7], vcc
	s_cbranch_execz .LBB0_530
	s_load_dwordx2 s[12:13], s[36:37], 0x0
	v_ashrrev_i32_e32 v7, 31, v6
	v_lshlrev_b64 v[10:11], 12, v[6:7]
	v_lshlrev_b64 v[2:3], 11, v[6:7]
	v_lshl_or_b32 v10, v8, 4, v10
	v_cmp_eq_u32_e32 vcc, 0, v8
	v_mov_b64_e32 v[0:1], 0x8700000
	s_ashr_i32 s5, s4, 31
	v_lshl_or_b32 v2, v8, 3, v2
	s_waitcnt lgkmcnt(0)
	v_lshl_add_u64 v[8:9], s[12:13], 0, v[10:11]
	s_mov_b64 s[12:13], 0xc00
	v_lshl_add_u64 v[0:1], v[6:7], 2, v[0:1]
	s_lshl_b64 s[8:9], s[4:5], 2
	s_lshl_b64 s[10:11], s[4:5], 11
	v_lshl_add_u64 v[8:9], v[8:9], 0, s[12:13]
	s_lshl_b64 s[12:13], s[4:5], 12
	s_mov_b64 s[14:15], 0
	s_branch .LBB0_528
